# FFN-up epilogue: second batch of conv tap/bias loads issued with the first batch into free VGPRs (no second exposed L2 wait); exchange barrier moved behind the load issue
# speedup vs baseline: 1.0058x; 1.0058x over previous
.LBB0_1260:
	s_or_b64 exec, exec, s[4:5]
	v_lshl_add_u32 v176, s8, 7, v160
	v_ashrrev_i32_e32 v177, 31, v176
	v_lshlrev_b64 v[128:129], 2, v[176:177]
	v_lshl_add_u64 v[180:181], s[16:17], 0, v[128:129]
	v_add_co_u32_e32 v136, vcc, 0xb000, v180
	s_mov_b32 s4, 0x16000
	s_nop 0
	v_addc_co_u32_e32 v137, vcc, 0, v181, vcc
	v_add_co_u32_e32 v184, vcc, s4, v180
	v_lshl_add_u64 v[178:179], s[20:21], 0, v[128:129]
	s_nop 0
	v_addc_co_u32_e32 v185, vcc, 0, v181, vcc
	s_movk_i32 s4, 0x5000
	v_add_co_u32_e32 v182, vcc, s4, v178
	s_nop 0
	s_nop 0
	v_addc_co_u32_e32 v183, vcc, 0, v179, vcc
	v_add_co_u32_e32 v186, vcc, s4, v180
	s_mov_b32 s4, 0x10000
	s_nop 0
	v_addc_co_u32_e32 v187, vcc, 0, v181, vcc
	v_add_co_u32_e32 v188, vcc, s4, v180
	s_mov_b32 s4, 0x1b000
	s_nop 0
	v_addc_co_u32_e32 v189, vcc, 0, v181, vcc
	global_load_dwordx4 v[128:131], v[178:179], off
	global_load_dwordx4 v[132:135], v[180:181], off
	global_load_dwordx4 v[148:151], v[136:137], off
	global_load_dwordx4 v[216:219], v[136:137], off offset:16
	global_load_dwordx4 v[152:155], v[184:185], off
	s_nop 0
	global_load_dwordx4 v[136:139], v[182:183], off offset:2048
	global_load_dwordx4 v[140:143], v[186:187], off offset:2048
	global_load_dwordx4 v[144:147], v[188:189], off offset:2048
	v_add_co_u32_e32 v190, vcc, s4, v180
	v_readlane_b32 s4, v254, 40
	s_nop 0
	v_addc_co_u32_e32 v191, vcc, 0, v181, vcc
	global_load_dwordx4 v[156:159], v[190:191], off offset:2048
	global_load_dwordx4 v[224:227], v[178:179], off offset:16
	global_load_dwordx4 v[228:231], v[180:181], off offset:16
	global_load_dwordx4 v[232:235], v[184:185], off offset:16
	global_load_dwordx4 v[236:239], v[188:189], off offset:2064
	global_load_dwordx4 v[240:243], v[182:183], off offset:2064
	global_load_dwordx4 v[244:247], v[186:187], off offset:2064
	global_load_dwordx4 v[248:251], v[190:191], off offset:2064
	v_lshlrev_b32_e32 v204, 2, v160
	v_or_b32_e32 v161, s4, v201
	v_add_u32_e32 v203, s87, v204
	v_readlane_b32 s4, v254, 42
	v_cmp_eq_u32_e64 s[8:9], 0, v161
	s_waitcnt lgkmcnt(0)
	s_barrier
	ds_read_b128 v[160:163], v203
	v_add_u32_e32 v202, s4, v204
	ds_read_b128 v[172:175], v202
	ds_read_b128 v[164:167], v203 offset:512
	ds_read_b128 v[168:171], v202 offset:512
	s_lshl_b32 s25, s14, 2
	s_mul_hi_i32 s4, s25, 0xb000
	s_waitcnt lgkmcnt(0)
	v_mov_b32_dpp v160, v112 row_shr:1 row_mask:0xf bank_mask:0xf
	v_mov_b32_dpp v161, v113 row_shr:1 row_mask:0xf bank_mask:0xf
	v_mov_b32_dpp v162, v114 row_shr:1 row_mask:0xf bank_mask:0xf
	v_mov_b32_dpp v163, v115 row_shr:1 row_mask:0xf bank_mask:0xf
	v_mov_b32_dpp v164, v96 row_shr:1 row_mask:0xf bank_mask:0xf
	v_mov_b32_dpp v165, v97 row_shr:1 row_mask:0xf bank_mask:0xf
	v_mov_b32_dpp v166, v98 row_shr:1 row_mask:0xf bank_mask:0xf
	v_mov_b32_dpp v167, v99 row_shr:1 row_mask:0xf bank_mask:0xf
	v_mov_b32_dpp v172, v124 row_shl:1 row_mask:0xf bank_mask:0xf
	v_mov_b32_dpp v173, v125 row_shl:1 row_mask:0xf bank_mask:0xf
	v_mov_b32_dpp v174, v126 row_shl:1 row_mask:0xf bank_mask:0xf
	v_mov_b32_dpp v175, v127 row_shl:1 row_mask:0xf bank_mask:0xf
	v_mov_b32_dpp v168, v108 row_shl:1 row_mask:0xf bank_mask:0xf
	v_mov_b32_dpp v169, v109 row_shl:1 row_mask:0xf bank_mask:0xf
	v_mov_b32_dpp v170, v110 row_shl:1 row_mask:0xf bank_mask:0xf
	v_mov_b32_dpp v171, v111 row_shl:1 row_mask:0xf bank_mask:0xf
	s_mul_i32 s5, s25, 0xb000
	s_waitcnt vmcnt(0)
	v_pk_fma_f32 v[206:207], v[124:125], v[148:149], v[128:129]
	v_pk_fma_f32 v[208:209], v[126:127], v[150:151], v[130:131]
	v_pk_fma_f32 v[160:161], v[132:133], v[160:161], v[206:207]
	v_pk_fma_f32 v[162:163], v[134:135], v[162:163], v[208:209]
	v_pk_fma_f32 v[206:207], v[108:109], v[144:145], v[136:137]
	v_pk_fma_f32 v[208:209], v[110:111], v[146:147], v[138:139]
	v_pk_fma_f32 v[164:165], v[140:141], v[164:165], v[206:207]
	v_pk_fma_f32 v[166:167], v[142:143], v[166:167], v[208:209]
	v_pk_fma_f32 v[160:161], v[120:121], v[152:153], v[160:161]
	v_pk_fma_f32 v[162:163], v[122:123], v[154:155], v[162:163]
	v_pk_fma_f32 v[164:165], v[104:105], v[156:157], v[164:165]
	v_pk_fma_f32 v[166:167], v[106:107], v[158:159], v[166:167]
	s_and_saveexec_b64 s[34:35], s[8:9]
	s_mov_b32 s75, 0x20000
	s_cbranch_execz .LBB0_1262
	s_add_u32 s36, s83, s5
	s_addc_u32 s37, s84, s4
	v_lshl_add_u64 v[206:207], v[176:177], 2, s[36:37]
	v_add_co_u32_e32 v208, vcc, 0x5000, v206
	global_store_dwordx4 v[206:207], v[160:163], off
	s_nop 0
	v_addc_co_u32_e32 v209, vcc, 0, v207, vcc
	global_store_dwordx4 v[208:209], v[164:167], off offset:2048
	v_add_co_u32_e32 v208, vcc, 0xb000, v206
	s_nop 1
	v_addc_co_u32_e32 v209, vcc, 0, v207, vcc
	v_add_co_u32_e32 v206, vcc, 0x10000, v206
	global_store_dwordx4 v[208:209], v[124:127], off
	s_nop 0
	v_addc_co_u32_e32 v207, vcc, 0, v207, vcc
	global_store_dwordx4 v[206:207], v[108:111], off offset:2048

.LBB0_1264:
	s_or_b64 exec, exec, s[34:35]
	v_pk_fma_f32 v[102:103], v[88:89], v[148:149], v[128:129]
	v_pk_fma_f32 v[98:99], v[92:93], v[148:149], v[128:129]
	v_pk_fma_f32 v[92:93], v[92:93], v[132:133], v[102:103]
	v_pk_fma_f32 v[98:99], v[132:133], v[118:119], v[98:99]
	v_pk_fma_f32 v[92:93], v[84:85], v[152:153], v[92:93]
	v_pk_fma_f32 v[84:85], v[84:85], v[148:149], v[128:129]
	v_pk_fma_f32 v[98:99], v[88:89], v[152:153], v[98:99]
	v_pk_fma_f32 v[84:85], v[88:89], v[132:133], v[84:85]
	v_pk_fma_f32 v[88:89], v[90:91], v[150:151], v[130:131]
	v_pk_fma_f32 v[80:81], v[80:81], v[152:153], v[84:85]
	v_pk_fma_f32 v[84:85], v[94:95], v[150:151], v[130:131]
	v_pk_fma_f32 v[88:89], v[94:95], v[134:135], v[88:89]
	v_pk_fma_f32 v[84:85], v[134:135], v[120:121], v[84:85]
	v_pk_fma_f32 v[88:89], v[86:87], v[154:155], v[88:89]
	v_pk_fma_f32 v[86:87], v[86:87], v[150:151], v[130:131]
	v_pk_fma_f32 v[84:85], v[90:91], v[154:155], v[84:85]
	v_pk_fma_f32 v[86:87], v[90:91], v[134:135], v[86:87]
	v_pk_fma_f32 v[90:91], v[72:73], v[144:145], v[136:137]
	v_pk_fma_f32 v[82:83], v[82:83], v[154:155], v[86:87]
	v_pk_fma_f32 v[86:87], v[76:77], v[144:145], v[136:137]
	v_pk_fma_f32 v[76:77], v[76:77], v[140:141], v[90:91]
	v_pk_fma_f32 v[86:87], v[140:141], v[122:123], v[86:87]
	v_pk_fma_f32 v[76:77], v[68:69], v[156:157], v[76:77]
	v_pk_fma_f32 v[68:69], v[68:69], v[144:145], v[136:137]
	v_pk_fma_f32 v[86:87], v[72:73], v[156:157], v[86:87]
	v_pk_fma_f32 v[68:69], v[72:73], v[140:141], v[68:69]
	s_nop 0
	v_pk_fma_f32 v[72:73], v[64:65], v[156:157], v[68:69]
	v_pk_fma_f32 v[64:65], v[78:79], v[146:147], v[138:139]
	s_nop 0
	v_pk_fma_f32 v[64:65], v[142:143], v[124:125], v[64:65]
	s_nop 0
	v_pk_fma_f32 v[68:69], v[74:75], v[158:159], v[64:65]
	v_pk_fma_f32 v[64:65], v[74:75], v[146:147], v[138:139]
	s_nop 0
	v_pk_fma_f32 v[64:65], v[78:79], v[142:143], v[64:65]
	s_nop 0
	v_pk_fma_f32 v[78:79], v[70:71], v[158:159], v[64:65]
	v_exp_f32_e32 v64, v86
	v_exp_f32_e32 v65, v87
	v_pk_fma_f32 v[70:71], v[70:71], v[146:147], v[138:139]
	v_pk_add_f32 v[64:65], v[64:65], 1.0 op_sel_hi:[1,0]
	v_pk_fma_f32 v[70:71], v[74:75], v[142:143], v[70:71]
	v_rcp_f32_e32 v64, v64
	v_pk_fma_f32 v[66:67], v[66:67], v[158:159], v[70:71]
	v_exp_f32_e32 v70, v68
	v_exp_f32_e32 v71, v69
	v_rcp_f32_e32 v65, v65
	v_pk_mul_f32 v[74:75], v[98:99], v[86:87]
	v_pk_mul_f32 v[68:69], v[84:85], v[68:69]
	v_pk_add_f32 v[70:71], v[70:71], 1.0 op_sel_hi:[1,0]
	v_pk_mul_f32 v[64:65], v[74:75], v[64:65]
	v_rcp_f32_e32 v70, v70
	v_rcp_f32_e32 v71, v71
	v_exp_f32_e32 v74, v76
	v_exp_f32_e32 v75, v77
	v_cvt_pk_bf16_f32 v64, v64, v65
	v_pk_mul_f32 v[68:69], v[68:69], v[70:71]
	v_exp_f32_e32 v70, v78
	v_exp_f32_e32 v71, v79
	v_cvt_pk_bf16_f32 v65, v68, v69
	v_pk_add_f32 v[68:69], v[74:75], 1.0 op_sel_hi:[1,0]
	v_pk_mul_f32 v[74:75], v[92:93], v[76:77]
	v_rcp_f32_e32 v68, v68
	v_rcp_f32_e32 v69, v69
	v_pk_add_f32 v[70:71], v[70:71], 1.0 op_sel_hi:[1,0]
	v_pk_mul_f32 v[76:77], v[88:89], v[78:79]
	v_rcp_f32_e32 v70, v70
	v_rcp_f32_e32 v71, v71
	v_pk_mul_f32 v[68:69], v[74:75], v[68:69]
	v_exp_f32_e32 v74, v72
	v_exp_f32_e32 v75, v73
	v_pk_mul_f32 v[70:71], v[76:77], v[70:71]
	v_cvt_pk_bf16_f32 v68, v68, v69
	v_pk_mul_f32 v[72:73], v[80:81], v[72:73]
	v_cvt_pk_bf16_f32 v69, v70, v71
	v_pk_add_f32 v[70:71], v[74:75], 1.0 op_sel_hi:[1,0]
	v_exp_f32_e32 v74, v66
	v_rcp_f32_e32 v70, v70
	v_rcp_f32_e32 v71, v71
	v_exp_f32_e32 v75, v67
	v_pk_mul_f32 v[66:67], v[82:83], v[66:67]
	v_pk_mul_f32 v[70:71], v[72:73], v[70:71]
	s_nop 0
	v_cvt_pk_bf16_f32 v72, v70, v71
	v_pk_add_f32 v[70:71], v[74:75], 1.0 op_sel_hi:[1,0]
	v_exp_f32_e32 v74, v114
	v_rcp_f32_e32 v70, v70
	v_rcp_f32_e32 v71, v71
	v_exp_f32_e32 v75, v115
	v_pk_mul_f32 v[66:67], v[66:67], v[70:71]
	v_exp_f32_e32 v70, v116
	v_exp_f32_e32 v71, v117
	v_cvt_pk_bf16_f32 v73, v66, v67
	v_pk_add_f32 v[66:67], v[74:75], 1.0 op_sel_hi:[1,0]
	v_pk_mul_f32 v[74:75], v[110:111], v[114:115]
	v_rcp_f32_e32 v66, v66
	v_rcp_f32_e32 v67, v67
	v_pk_add_f32 v[70:71], v[70:71], 1.0 op_sel_hi:[1,0]
	v_pk_mul_f32 v[66:67], v[74:75], v[66:67]
	v_rcp_f32_e32 v70, v70
	v_rcp_f32_e32 v71, v71
	v_cvt_pk_bf16_f32 v76, v66, v67
	v_pk_mul_f32 v[66:67], v[112:113], v[116:117]
	s_nop 0
	v_pk_mul_f32 v[66:67], v[66:67], v[70:71]
	s_nop 0
	v_cvt_pk_bf16_f32 v77, v66, v67
	ds_read_b128 v[128:131], v203 offset:16
	ds_read_b128 v[132:135], v202 offset:16
	ds_read_b128 v[136:139], v203 offset:528
	ds_read_b128 v[140:143], v202 offset:528
	s_waitcnt lgkmcnt(3)
	v_mov_b32_dpp v128, v48 row_shr:1 row_mask:0xf bank_mask:0xf
	v_mov_b32_dpp v129, v49 row_shr:1 row_mask:0xf bank_mask:0xf
	v_mov_b32_dpp v130, v50 row_shr:1 row_mask:0xf bank_mask:0xf
	v_mov_b32_dpp v131, v51 row_shr:1 row_mask:0xf bank_mask:0xf
	s_waitcnt lgkmcnt(1)
	v_mov_b32_dpp v136, v32 row_shr:1 row_mask:0xf bank_mask:0xf
	v_mov_b32_dpp v137, v33 row_shr:1 row_mask:0xf bank_mask:0xf
	v_mov_b32_dpp v138, v34 row_shr:1 row_mask:0xf bank_mask:0xf
	v_mov_b32_dpp v139, v35 row_shr:1 row_mask:0xf bank_mask:0xf
	v_mov_b32_dpp v132, v60 row_shl:1 row_mask:0xf bank_mask:0xf
	v_mov_b32_dpp v133, v61 row_shl:1 row_mask:0xf bank_mask:0xf
	v_mov_b32_dpp v134, v62 row_shl:1 row_mask:0xf bank_mask:0xf
	v_mov_b32_dpp v135, v63 row_shl:1 row_mask:0xf bank_mask:0xf
	s_waitcnt lgkmcnt(0)
	v_mov_b32_dpp v140, v44 row_shl:1 row_mask:0xf bank_mask:0xf
	v_mov_b32_dpp v141, v45 row_shl:1 row_mask:0xf bank_mask:0xf
	v_mov_b32_dpp v142, v46 row_shl:1 row_mask:0xf bank_mask:0xf
	v_mov_b32_dpp v143, v47 row_shl:1 row_mask:0xf bank_mask:0xf
	v_pk_fma_f32 v[66:67], v[60:61], v[216:217], v[224:225]
	v_pk_fma_f32 v[66:67], v[228:229], v[128:129], v[66:67]
	v_pk_fma_f32 v[128:129], v[56:57], v[232:233], v[66:67]
	v_pk_fma_f32 v[66:67], v[62:63], v[218:219], v[226:227]
	s_nop 0
	v_pk_fma_f32 v[66:67], v[230:231], v[130:131], v[66:67]
	s_nop 0
	v_pk_fma_f32 v[130:131], v[58:59], v[234:235], v[66:67]
	v_pk_fma_f32 v[66:67], v[44:45], v[236:237], v[240:241]
	v_pk_fma_f32 v[66:67], v[244:245], v[136:137], v[66:67]
	v_pk_fma_f32 v[136:137], v[40:41], v[248:249], v[66:67]
	v_pk_fma_f32 v[66:67], v[46:47], v[238:239], v[242:243]
	s_nop 0
	v_pk_fma_f32 v[66:67], v[246:247], v[138:139], v[66:67]
	s_nop 0
	v_pk_fma_f32 v[138:139], v[42:43], v[250:251], v[66:67]
	s_and_saveexec_b64 s[34:35], s[8:9]
	s_cbranch_execz .LBB0_1266
	s_add_u32 s8, s83, s5
	s_addc_u32 s9, s84, s4
	v_lshl_add_u64 v[66:67], v[176:177], 2, s[8:9]
	v_add_co_u32_e32 v70, vcc, 0x5000, v66
	global_store_dwordx4 v[66:67], v[128:131], off offset:16
	s_nop 0
	v_addc_co_u32_e32 v71, vcc, 0, v67, vcc
	global_store_dwordx4 v[70:71], v[136:139], off offset:2064
	v_add_co_u32_e32 v70, vcc, 0xb000, v66
	s_nop 1
	v_addc_co_u32_e32 v71, vcc, 0, v67, vcc
	v_add_co_u32_e32 v66, vcc, 0x10000, v66
	global_store_dwordx4 v[70:71], v[60:63], off offset:16
	s_nop 0
	v_addc_co_u32_e32 v67, vcc, 0, v67, vcc
	global_store_dwordx4 v[66:67], v[44:47], off offset:2064
.LBB0_1266:
	s_or_b64 exec, exec, s[34:35]
	v_pk_fma_f32 v[66:67], v[56:57], v[216:217], v[224:225]
	s_nop 0
	v_pk_fma_f32 v[60:61], v[60:61], v[228:229], v[66:67]
	v_pk_fma_f32 v[66:67], v[52:53], v[216:217], v[224:225]
	v_pk_fma_f32 v[60:61], v[52:53], v[232:233], v[60:61]
	v_pk_fma_f32 v[56:57], v[56:57], v[228:229], v[66:67]
	s_nop 0
	v_pk_fma_f32 v[56:57], v[48:49], v[232:233], v[56:57]
	v_pk_fma_f32 v[48:49], v[48:49], v[216:217], v[224:225]
	s_nop 0
	v_pk_fma_f32 v[48:49], v[52:53], v[228:229], v[48:49]
	v_pk_fma_f32 v[52:53], v[58:59], v[218:219], v[226:227]
	v_pk_fma_f32 v[48:49], v[232:233], v[132:133], v[48:49]
	v_pk_fma_f32 v[52:53], v[62:63], v[230:231], v[52:53]
	v_pk_fma_f32 v[62:63], v[54:55], v[218:219], v[226:227]
	v_pk_fma_f32 v[52:53], v[54:55], v[234:235], v[52:53]
	v_pk_fma_f32 v[58:59], v[58:59], v[230:231], v[62:63]
	s_nop 0
	v_pk_fma_f32 v[58:59], v[50:51], v[234:235], v[58:59]
	v_pk_fma_f32 v[50:51], v[50:51], v[218:219], v[226:227]
	s_nop 0
	v_pk_fma_f32 v[50:51], v[54:55], v[230:231], v[50:51]
	v_pk_fma_f32 v[54:55], v[40:41], v[236:237], v[240:241]
	v_pk_fma_f32 v[50:51], v[234:235], v[134:135], v[50:51]
	v_pk_fma_f32 v[44:45], v[44:45], v[244:245], v[54:55]
	v_pk_fma_f32 v[54:55], v[36:37], v[236:237], v[240:241]
	v_pk_fma_f32 v[44:45], v[36:37], v[248:249], v[44:45]
	v_pk_fma_f32 v[40:41], v[40:41], v[244:245], v[54:55]
	v_pk_mul_f32 v[54:55], v[128:129], v[136:137]
	v_pk_fma_f32 v[40:41], v[32:33], v[248:249], v[40:41]
	v_pk_fma_f32 v[32:33], v[32:33], v[236:237], v[240:241]
	s_nop 0
	v_pk_fma_f32 v[32:33], v[36:37], v[244:245], v[32:33]
	v_pk_fma_f32 v[36:37], v[42:43], v[238:239], v[242:243]
	v_pk_fma_f32 v[32:33], v[248:249], v[140:141], v[32:33]
	v_pk_fma_f32 v[36:37], v[46:47], v[246:247], v[36:37]
	v_pk_fma_f32 v[46:47], v[38:39], v[238:239], v[242:243]
	v_pk_fma_f32 v[36:37], v[38:39], v[250:251], v[36:37]
	v_pk_fma_f32 v[42:43], v[42:43], v[246:247], v[46:47]
	v_exp_f32_e32 v46, v136
	v_exp_f32_e32 v47, v137
	v_pk_fma_f32 v[42:43], v[34:35], v[250:251], v[42:43]
	v_pk_fma_f32 v[34:35], v[34:35], v[238:239], v[242:243]
	s_nop 0
	v_pk_fma_f32 v[34:35], v[38:39], v[246:247], v[34:35]
	v_pk_add_f32 v[38:39], v[46:47], 1.0 op_sel_hi:[1,0]
	v_exp_f32_e32 v46, v138
	v_rcp_f32_e32 v38, v38
	v_rcp_f32_e32 v39, v39
	v_exp_f32_e32 v47, v139
	v_pk_fma_f32 v[34:35], v[250:251], v[142:143], v[34:35]
	v_pk_mul_f32 v[38:39], v[54:55], v[38:39]
	s_nop 0
	v_cvt_pk_bf16_f32 v98, v38, v39
	v_pk_add_f32 v[38:39], v[46:47], 1.0 op_sel_hi:[1,0]
	v_exp_f32_e32 v46, v44
	v_rcp_f32_e32 v38, v38
	v_rcp_f32_e32 v39, v39
	v_exp_f32_e32 v47, v45
	v_pk_mul_f32 v[54:55], v[130:131], v[138:139]
	v_pk_mul_f32 v[44:45], v[60:61], v[44:45]
	v_pk_mul_f32 v[38:39], v[54:55], v[38:39]
	s_nop 0
	v_cvt_pk_bf16_f32 v99, v38, v39
	v_pk_add_f32 v[38:39], v[46:47], 1.0 op_sel_hi:[1,0]
	v_exp_f32_e32 v46, v36
	v_rcp_f32_e32 v38, v38
	v_rcp_f32_e32 v39, v39
	v_exp_f32_e32 v47, v37
	v_pk_mul_f32 v[36:37], v[52:53], v[36:37]
	v_pk_mul_f32 v[38:39], v[44:45], v[38:39]
	s_nop 0
	v_cvt_pk_bf16_f32 v102, v38, v39
	v_pk_add_f32 v[38:39], v[46:47], 1.0 op_sel_hi:[1,0]
	v_exp_f32_e32 v44, v40
	v_rcp_f32_e32 v38, v38
	v_rcp_f32_e32 v39, v39
	v_exp_f32_e32 v45, v41
	v_pk_mul_f32 v[40:41], v[56:57], v[40:41]
	v_pk_mul_f32 v[36:37], v[36:37], v[38:39]
	s_nop 0
	v_cvt_pk_bf16_f32 v103, v36, v37
	v_pk_add_f32 v[36:37], v[44:45], 1.0 op_sel_hi:[1,0]
	v_exp_f32_e32 v38, v42
	v_rcp_f32_e32 v36, v36
	v_rcp_f32_e32 v37, v37
	v_exp_f32_e32 v39, v43
	v_pk_mul_f32 v[36:37], v[40:41], v[36:37]
	s_nop 0
	v_cvt_pk_bf16_f32 v106, v36, v37
	v_pk_add_f32 v[36:37], v[38:39], 1.0 op_sel_hi:[1,0]
	v_exp_f32_e32 v38, v32
	v_rcp_f32_e32 v36, v36
	v_rcp_f32_e32 v37, v37
	v_exp_f32_e32 v39, v33
	v_pk_mul_f32 v[40:41], v[58:59], v[42:43]
	v_pk_mul_f32 v[32:33], v[48:49], v[32:33]
	v_pk_mul_f32 v[36:37], v[40:41], v[36:37]
	v_pk_fma_f32 v[48:49], v[8:9], v[216:217], v[224:225]
	v_cvt_pk_bf16_f32 v107, v36, v37
	v_pk_add_f32 v[36:37], v[38:39], 1.0 op_sel_hi:[1,0]
	v_exp_f32_e32 v38, v34
	v_exp_f32_e32 v39, v35
	v_rcp_f32_e32 v36, v36
	v_rcp_f32_e32 v37, v37
	v_pk_fma_f32 v[48:49], v[20:21], v[228:229], v[48:49]
	v_pk_add_f32 v[38:39], v[38:39], 1.0 op_sel_hi:[1,0]
	v_pk_mul_f32 v[32:33], v[32:33], v[36:37]
	v_rcp_f32_e32 v38, v38
	v_rcp_f32_e32 v39, v39
	v_cvt_pk_bf16_f32 v110, v32, v33
	v_pk_mul_f32 v[32:33], v[50:51], v[34:35]
	s_nop 0
	v_pk_mul_f32 v[32:33], v[32:33], v[38:39]
	s_nop 0
	v_cvt_pk_bf16_f32 v111, v32, v33
	ds_read_b128 v[40:43], v160 offset:16
	ds_read_b128 v[32:35], v161 offset:16
	ds_read_b128 v[44:47], v160 offset:528
	ds_read_b128 v[36:39], v161 offset:528
	s_waitcnt lgkmcnt(3)
	v_mov_b32_dpp v40, v8 row_shr:1 row_mask:0xf bank_mask:0xf
	s_waitcnt lgkmcnt(2)
	v_mov_b32_dpp v32, v28 row_shl:1 row_mask:0xf bank_mask:0xf
	v_mov_b32_dpp v33, v29 row_shl:1 row_mask:0xf bank_mask:0xf
	v_pk_fma_f32 v[32:33], v[232:233], v[32:33], v[48:49]
	v_pk_fma_f32 v[48:49], v[10:11], v[218:219], v[226:227]
	v_mov_b32_dpp v34, v30 row_shl:1 row_mask:0xf bank_mask:0xf
	v_mov_b32_dpp v35, v31 row_shl:1 row_mask:0xf bank_mask:0xf
	v_pk_fma_f32 v[48:49], v[22:23], v[230:231], v[48:49]
	s_waitcnt lgkmcnt(0)
	v_mov_b32_dpp v36, v24 row_shl:1 row_mask:0xf bank_mask:0xf
	v_pk_fma_f32 v[34:35], v[234:235], v[34:35], v[48:49]
	v_pk_fma_f32 v[48:49], v[0:1], v[236:237], v[240:241]
	v_mov_b32_dpp v37, v25 row_shl:1 row_mask:0xf bank_mask:0xf
	v_pk_fma_f32 v[48:49], v[4:5], v[244:245], v[48:49]
	v_mov_b32_dpp v38, v26 row_shl:1 row_mask:0xf bank_mask:0xf
	v_pk_fma_f32 v[36:37], v[248:249], v[36:37], v[48:49]
	v_pk_fma_f32 v[48:49], v[2:3], v[238:239], v[242:243]
	v_mov_b32_dpp v39, v27 row_shl:1 row_mask:0xf bank_mask:0xf
	v_pk_fma_f32 v[48:49], v[6:7], v[246:247], v[48:49]
	v_mov_b32_dpp v41, v9 row_shr:1 row_mask:0xf bank_mask:0xf
	v_mov_b32_dpp v42, v10 row_shr:1 row_mask:0xf bank_mask:0xf
	v_mov_b32_dpp v43, v11 row_shr:1 row_mask:0xf bank_mask:0xf
	v_mov_b32_dpp v44, v0 row_shr:1 row_mask:0xf bank_mask:0xf
	v_mov_b32_dpp v45, v1 row_shr:1 row_mask:0xf bank_mask:0xf
	v_mov_b32_dpp v46, v2 row_shr:1 row_mask:0xf bank_mask:0xf
	v_mov_b32_dpp v47, v3 row_shr:1 row_mask:0xf bank_mask:0xf
	v_pk_fma_f32 v[38:39], v[250:251], v[38:39], v[48:49]
	s_and_saveexec_b64 s[8:9], s[10:11]
	s_cbranch_execz .LBB0_1268
	s_add_u32 s4, s83, s27
	s_addc_u32 s5, s84, s25
	v_lshl_add_u64 v[48:49], v[176:177], 2, s[4:5]
	v_add_co_u32_e32 v50, vcc, 0x5000, v48
	global_store_dwordx4 v[48:49], v[32:35], off offset:16
	s_nop 0
	v_addc_co_u32_e32 v51, vcc, 0, v49, vcc
	global_store_dwordx4 v[50:51], v[36:39], off offset:2064
	v_add_co_u32_e32 v50, vcc, 0xb000, v48
	s_nop 1
	v_addc_co_u32_e32 v51, vcc, 0, v49, vcc
	v_add_co_u32_e32 v48, vcc, 0x10000, v48
	global_store_dwordx4 v[50:51], v[8:11], off offset:16
	s_nop 0
	v_addc_co_u32_e32 v49, vcc, 0, v49, vcc
	global_store_dwordx4 v[48:49], v[0:3], off offset:2064
.LBB0_1268:
	s_or_b64 exec, exec, s[8:9]
	v_pk_fma_f32 v[48:49], v[6:7], v[238:239], v[242:243]
	s_movk_i32 s8, 0x1600
	v_pk_fma_f32 v[48:49], v[14:15], v[246:247], v[48:49]
	s_mul_i32 s4, s14, 0x2c0000
	v_pk_fma_f32 v[2:3], v[2:3], v[250:251], v[48:49]
	v_pk_fma_f32 v[48:49], v[14:15], v[238:239], v[242:243]
	s_mul_hi_i32 s5, s14, 0x2c0000
	v_pk_fma_f32 v[48:49], v[26:27], v[246:247], v[48:49]
	v_pk_fma_f32 v[26:27], v[26:27], v[238:239], v[242:243]
	v_pk_fma_f32 v[6:7], v[6:7], v[250:251], v[48:49]
	v_pk_fma_f32 v[26:27], v[246:247], v[46:47], v[26:27]
	s_add_u32 s4, s81, s4
	v_pk_fma_f32 v[14:15], v[14:15], v[250:251], v[26:27]
	v_pk_fma_f32 v[26:27], v[4:5], v[236:237], v[240:241]
	s_addc_u32 s5, s82, s5
	v_pk_fma_f32 v[26:27], v[12:13], v[244:245], v[26:27]
	s_andn2_b64 vcc, exec, s[22:23]
	v_pk_fma_f32 v[0:1], v[0:1], v[248:249], v[26:27]
	v_pk_fma_f32 v[26:27], v[12:13], v[236:237], v[240:241]
	s_nop 0
	v_pk_fma_f32 v[26:27], v[24:25], v[244:245], v[26:27]
	v_pk_fma_f32 v[24:25], v[24:25], v[236:237], v[240:241]
	v_pk_fma_f32 v[4:5], v[4:5], v[248:249], v[26:27]
	v_pk_fma_f32 v[24:25], v[244:245], v[44:45], v[24:25]
	v_pk_fma_f32 v[26:27], v[28:29], v[216:217], v[224:225]
	v_pk_fma_f32 v[12:13], v[12:13], v[248:249], v[24:25]
	v_pk_fma_f32 v[24:25], v[22:23], v[218:219], v[226:227]
	v_pk_fma_f32 v[26:27], v[228:229], v[40:41], v[26:27]
	v_pk_fma_f32 v[24:25], v[18:19], v[230:231], v[24:25]
	s_nop 0
	v_pk_fma_f32 v[10:11], v[10:11], v[234:235], v[24:25]
	v_pk_fma_f32 v[24:25], v[18:19], v[218:219], v[226:227]
	s_nop 0
	v_pk_fma_f32 v[24:25], v[30:31], v[230:231], v[24:25]
	s_nop 0
	v_pk_fma_f32 v[22:23], v[22:23], v[234:235], v[24:25]
	v_pk_fma_f32 v[24:25], v[30:31], v[218:219], v[226:227]
	s_nop 0
	v_pk_fma_f32 v[24:25], v[230:231], v[42:43], v[24:25]
	s_nop 0
	v_pk_fma_f32 v[18:19], v[18:19], v[234:235], v[24:25]
	v_pk_fma_f32 v[24:25], v[20:21], v[216:217], v[224:225]
	s_nop 0
	v_pk_fma_f32 v[24:25], v[16:17], v[228:229], v[24:25]
	s_nop 0
	v_pk_fma_f32 v[8:9], v[8:9], v[232:233], v[24:25]
	v_pk_fma_f32 v[24:25], v[16:17], v[216:217], v[224:225]
	v_pk_fma_f32 v[16:17], v[16:17], v[232:233], v[26:27]
	v_pk_fma_f32 v[24:25], v[28:29], v[228:229], v[24:25]
	v_exp_f32_e32 v26, v14
	v_pk_fma_f32 v[20:21], v[20:21], v[232:233], v[24:25]
	v_exp_f32_e32 v24, v12
	v_exp_f32_e32 v25, v13
	v_exp_f32_e32 v27, v15
	v_pk_mul_f32 v[12:13], v[16:17], v[12:13]
	v_exp_f32_e32 v16, v4
	v_pk_add_f32 v[24:25], v[24:25], 1.0 op_sel_hi:[1,0]
	v_exp_f32_e32 v17, v5
	v_rcp_f32_e32 v24, v24
	v_rcp_f32_e32 v25, v25
	v_pk_mul_f32 v[14:15], v[18:19], v[14:15]
	v_pk_mul_f32 v[4:5], v[20:21], v[4:5]
	v_pk_mul_f32 v[12:13], v[12:13], v[24:25]
	s_nop 0
	v_cvt_pk_bf16_f32 v66, v12, v13
	v_pk_add_f32 v[12:13], v[26:27], 1.0 op_sel_hi:[1,0]
	s_nop 0
	v_rcp_f32_e32 v12, v12
	v_rcp_f32_e32 v13, v13
	s_nop 0
	v_pk_mul_f32 v[12:13], v[14:15], v[12:13]
	s_nop 0
	v_cvt_pk_bf16_f32 v67, v12, v13
	v_pk_add_f32 v[12:13], v[16:17], 1.0 op_sel_hi:[1,0]
	v_exp_f32_e32 v14, v6
	v_rcp_f32_e32 v12, v12
	v_rcp_f32_e32 v13, v13
	v_exp_f32_e32 v15, v7
	v_pk_mul_f32 v[6:7], v[22:23], v[6:7]
	v_pk_mul_f32 v[4:5], v[4:5], v[12:13]
	s_nop 0
	v_cvt_pk_bf16_f32 v70, v4, v5
	v_pk_add_f32 v[4:5], v[14:15], 1.0 op_sel_hi:[1,0]
	v_exp_f32_e32 v12, v0
	v_rcp_f32_e32 v4, v4
	v_rcp_f32_e32 v5, v5
	v_exp_f32_e32 v13, v1
	v_pk_mul_f32 v[0:1], v[8:9], v[0:1]
	v_pk_mul_f32 v[4:5], v[6:7], v[4:5]
	s_nop 0
	v_cvt_pk_bf16_f32 v71, v4, v5
	v_pk_add_f32 v[4:5], v[12:13], 1.0 op_sel_hi:[1,0]
	v_exp_f32_e32 v6, v2
	v_rcp_f32_e32 v4, v4
	v_rcp_f32_e32 v5, v5
	v_exp_f32_e32 v7, v3
	v_pk_mul_f32 v[2:3], v[10:11], v[2:3]
	v_pk_mul_f32 v[0:1], v[0:1], v[4:5]
	s_nop 0
	v_cvt_pk_bf16_f32 v74, v0, v1
	v_pk_add_f32 v[0:1], v[6:7], 1.0 op_sel_hi:[1,0]
	v_exp_f32_e32 v4, v36
	v_rcp_f32_e32 v0, v0
	v_rcp_f32_e32 v1, v1
	v_exp_f32_e32 v5, v37
	v_pk_mul_f32 v[0:1], v[2:3], v[0:1]
	v_exp_f32_e32 v2, v38
	v_exp_f32_e32 v3, v39
	v_cvt_pk_bf16_f32 v75, v0, v1
	v_pk_add_f32 v[0:1], v[4:5], 1.0 op_sel_hi:[1,0]
	v_pk_mul_f32 v[4:5], v[32:33], v[36:37]
	v_rcp_f32_e32 v0, v0
	v_rcp_f32_e32 v1, v1
	v_pk_add_f32 v[2:3], v[2:3], 1.0 op_sel_hi:[1,0]
	v_pk_mul_f32 v[0:1], v[4:5], v[0:1]
	v_rcp_f32_e32 v2, v2
	v_rcp_f32_e32 v3, v3
	v_cvt_pk_bf16_f32 v78, v0, v1
	v_pk_mul_f32 v[0:1], v[34:35], v[38:39]
	s_nop 0
	v_pk_mul_f32 v[0:1], v[0:1], v[2:3]
	s_nop 0
	v_cvt_pk_bf16_f32 v79, v0, v1
	v_lshl_or_b32 v0, v201, 2, s64
	v_mul_lo_u32 v0, v0, s8
	v_add_lshl_u32 v0, v0, v176, 1
	v_add_u32_e32 v1, 0x2c00, v0
	global_store_dwordx4 v1, v[100:103], s[4:5]
	v_add_u32_e32 v1, 0x5800, v0
	global_store_dwordx4 v1, v[104:107], s[4:5]
	v_add_u32_e32 v1, 0x8400, v0
	global_store_dwordx4 v1, v[108:111], s[4:5]
	v_add_u32_e32 v1, 0x160000, v0
	global_store_dwordx4 v1, v[64:67], s[4:5]
	v_add_u32_e32 v1, 0x162c00, v0
	global_store_dwordx4 v0, v[96:99], s[4:5]
	global_store_dwordx4 v1, v[68:71], s[4:5]
	v_add_u32_e32 v1, 0x165800, v0
	v_add_u32_e32 v0, 0x168400, v0
	global_store_dwordx4 v1, v[72:75], s[4:5]
	global_store_dwordx4 v0, v[76:79], s[4:5]
	s_mov_b64 s[4:5], -1
	s_cbranch_vccnz .LBB0_1245
	s_and_b64 vcc, exec, s[6:7]
	s_cbranch_vccnz .LBB0_1244
	s_barrier
	s_branch .LBB0_1244
